# k32 + weight-slab pair handshake through tagged 64-bit mailboxes (one round trip instead of returning atomicMax + arrival poll + reload), merged maxima broadcast through LDS
# speedup vs baseline: 1.0020x; 1.0020x over previous
.LBB0_9:
	s_or_b64 exec, exec, s[0:1]
	s_cmpk_lt_i32 s20, 0x2b0
	s_cselect_b32 s0, s78, 0x1c400000
	s_add_u32 s21, s14, s0
	s_addc_u32 s34, s15, 0
	s_lshl_b32 s0, s84, 6
	s_lshl_b32 s1, s82, 7
	s_and_b32 s0, s0, 0xffffff00
	s_and_b32 s1, s1, 0x80
	s_or_b32 s35, s0, s1
	s_add_u32 s0, s25, s30
	s_addc_u32 s1, s85, s31
	s_barrier
	ds_read_b32 v9, v10 offset:1024
	s_ashr_i32 s0, s35, 7
	v_or_b32_e32 v4, s83, v1
	s_ashr_i32 s1, s0, 31
	v_ashrrev_i32_e32 v150, 7, v4
	s_lshl_b64 s[0:1], s[0:1], 19
	v_ashrrev_i32_e32 v151, 31, v150
	s_add_u32 s0, s21, s0
	v_lshlrev_b64 v[150:151], 14, v[150:151]
	s_addc_u32 s1, s34, s1
	v_lshl_add_u64 v[150:151], s[0:1], 0, v[150:151]
	v_or_b32_e32 v149, s24, v12
	v_lshlrev_b32_e32 v4, 7, v149
	v_and_b32_e32 v149, 0x3800, v4
	v_or_b32_e32 v4, v149, v13
	v_lshl_add_u64 v[152:153], v[150:151], 0, v[4:5]
	s_add_i32 s20, s20, s3
	s_cmpk_lt_i32 s20, 0x560
	s_waitcnt vmcnt(0) lgkmcnt(0)
	v_max_f32_e32 v9, v9, v9
	v_max_f32_e32 v9, 0xda24260, v9
	v_div_scale_f32 v154, s[0:1], v9, v9, s79
	v_rcp_f32_e32 v155, v154
	v_div_scale_f32 v4, vcc, s79, v9, s79
	v_fma_f32 v156, -v154, v155, 1.0
	v_fmac_f32_e32 v155, v156, v155
	v_mul_f32_e32 v156, v4, v155
	v_fma_f32 v157, -v154, v156, v4
	v_fmac_f32_e32 v156, v157, v155
	v_fma_f32 v4, -v154, v156, v4
	v_div_fmas_f32 v4, v4, v155, v156
	v_div_fixup_f32 v9, v4, v9, s79
	v_fmaak_f32 v4, v25, v9, 0x4b400000
	v_fmaak_f32 v25, v148, v9, 0x4b400000
	v_fmaak_f32 v26, v26, v9, 0x4b400000
	v_fmaak_f32 v21, v21, v9, 0x4b400000
	v_fmaak_f32 v27, v27, v9, 0x4b400000
	v_fmaak_f32 v22, v22, v9, 0x4b400000
	v_fmaak_f32 v28, v28, v9, 0x4b400000
	v_fmaak_f32 v23, v23, v9, 0x4b400000
	v_fmaak_f32 v33, v33, v9, 0x4b400000
	v_fmaak_f32 v24, v24, v9, 0x4b400000
	v_fmaak_f32 v34, v34, v9, 0x4b400000
	v_fmaak_f32 v30, v30, v9, 0x4b400000
	v_fmaak_f32 v35, v35, v9, 0x4b400000
	v_fmaak_f32 v31, v31, v9, 0x4b400000
	v_fmaak_f32 v36, v36, v9, 0x4b400000
	v_fmaak_f32 v32, v32, v9, 0x4b400000
	v_perm_b32 v4, v4, v25, s80
	v_perm_b32 v21, v26, v21, s81
	v_fmaak_f32 v44, v44, v9, 0x4b400000
	v_fmaak_f32 v29, v29, v9, 0x4b400000
	v_fmaak_f32 v43, v43, v9, 0x4b400000
	v_fmaak_f32 v41, v41, v9, 0x4b400000
	v_fmaak_f32 v42, v42, v9, 0x4b400000
	v_fmaak_f32 v39, v39, v9, 0x4b400000
	v_fmaak_f32 v40, v40, v9, 0x4b400000
	v_fmaak_f32 v38, v38, v9, 0x4b400000
	v_fmaak_f32 v52, v52, v9, 0x4b400000
	v_fmaak_f32 v37, v37, v9, 0x4b400000
	v_fmaak_f32 v51, v51, v9, 0x4b400000
	v_fmaak_f32 v49, v49, v9, 0x4b400000
	v_fmaak_f32 v50, v50, v9, 0x4b400000
	v_fmaak_f32 v47, v47, v9, 0x4b400000
	v_fmaak_f32 v48, v48, v9, 0x4b400000
	v_fmaak_f32 v46, v46, v9, 0x4b400000
	v_fmaak_f32 v60, v60, v9, 0x4b400000
	v_fmaak_f32 v45, v45, v9, 0x4b400000
	v_perm_b32 v25, v27, v22, s80
	v_perm_b32 v23, v28, v23, s81
	v_perm_b32 v24, v33, v24, s80
	v_perm_b32 v26, v34, v30, s81
	v_perm_b32 v27, v35, v31, s80
	v_perm_b32 v28, v36, v32, s81
	v_or_b32_e32 v22, v21, v4
	v_fmaak_f32 v4, v59, v9, 0x4b400000
	v_fmaak_f32 v21, v57, v9, 0x4b400000
	v_perm_b32 v29, v44, v29, s80
	v_perm_b32 v30, v43, v41, s81
	v_perm_b32 v31, v42, v39, s80
	v_perm_b32 v32, v40, v38, s81
	v_perm_b32 v33, v52, v37, s80
	v_perm_b32 v34, v51, v49, s81
	v_perm_b32 v35, v50, v47, s80
	v_perm_b32 v36, v48, v46, s81
	v_perm_b32 v37, v60, v45, s80
	v_or_b32_e32 v23, v23, v25
	v_or_b32_e32 v24, v26, v24
	v_or_b32_e32 v25, v28, v27
	v_perm_b32 v4, v4, v21, s81
	v_or_b32_e32 v26, v30, v29
	v_or_b32_e32 v27, v32, v31
	v_or_b32_e32 v28, v34, v33
	v_or_b32_e32 v29, v36, v35
	global_store_dwordx4 v[152:153], v[22:25], off
	global_store_dwordx4 v[152:153], v[26:29], off offset:16
	v_fmaak_f32 v21, v55, v9, 0x4b400000
	v_or_b32_e32 v22, v4, v37
	v_fmaak_f32 v4, v58, v9, 0x4b400000
	v_perm_b32 v4, v4, v21, s80
	v_fmaak_f32 v21, v56, v9, 0x4b400000
	v_fmaak_f32 v23, v54, v9, 0x4b400000
	v_perm_b32 v21, v21, v23, s81
	v_or_b32_e32 v23, v21, v4
	v_fmaak_f32 v4, v68, v9, 0x4b400000
	v_fmaak_f32 v21, v53, v9, 0x4b400000
	v_perm_b32 v4, v4, v21, s80
	v_fmaak_f32 v21, v67, v9, 0x4b400000
	v_fmaak_f32 v24, v65, v9, 0x4b400000
	v_perm_b32 v21, v21, v24, s81
	v_or_b32_e32 v24, v21, v4
	v_fmaak_f32 v4, v66, v9, 0x4b400000
	v_fmaak_f32 v21, v63, v9, 0x4b400000
	v_perm_b32 v4, v4, v21, s80
	v_fmaak_f32 v21, v64, v9, 0x4b400000
	v_fmaak_f32 v25, v62, v9, 0x4b400000
	v_perm_b32 v21, v21, v25, s81
	v_or_b32_e32 v25, v21, v4
	v_or_b32_e32 v4, v149, v15
	v_lshl_add_u64 v[26:27], v[150:151], 0, v[4:5]
	v_fmaak_f32 v4, v76, v9, 0x4b400000
	v_fmaak_f32 v21, v61, v9, 0x4b400000
	global_store_dwordx4 v[26:27], v[22:25], off
	v_perm_b32 v4, v4, v21, s80
	v_fmaak_f32 v21, v75, v9, 0x4b400000
	v_fmaak_f32 v22, v73, v9, 0x4b400000
	v_perm_b32 v21, v21, v22, s81
	v_or_b32_e32 v22, v21, v4
	v_fmaak_f32 v4, v74, v9, 0x4b400000
	v_fmaak_f32 v21, v71, v9, 0x4b400000
	v_perm_b32 v4, v4, v21, s80
	v_fmaak_f32 v21, v72, v9, 0x4b400000
	v_fmaak_f32 v23, v70, v9, 0x4b400000
	v_perm_b32 v21, v21, v23, s81
	v_or_b32_e32 v23, v21, v4
	v_fmaak_f32 v4, v84, v9, 0x4b400000
	v_fmaak_f32 v21, v69, v9, 0x4b400000
	v_perm_b32 v4, v4, v21, s80
	v_fmaak_f32 v21, v83, v9, 0x4b400000
	v_fmaak_f32 v24, v81, v9, 0x4b400000
	v_perm_b32 v21, v21, v24, s81
	v_or_b32_e32 v24, v21, v4
	v_fmaak_f32 v4, v82, v9, 0x4b400000
	v_fmaak_f32 v21, v79, v9, 0x4b400000
	v_perm_b32 v4, v4, v21, s80
	v_fmaak_f32 v21, v80, v9, 0x4b400000
	v_fmaak_f32 v25, v78, v9, 0x4b400000
	v_perm_b32 v21, v21, v25, s81
	v_or_b32_e32 v25, v21, v4
	v_or_b32_e32 v4, v149, v16
	v_lshl_add_u64 v[28:29], v[150:151], 0, v[4:5]
	v_fmaak_f32 v4, v92, v9, 0x4b400000
	v_fmaak_f32 v21, v77, v9, 0x4b400000
	global_store_dwordx4 v[28:29], v[22:25], off
	v_perm_b32 v4, v4, v21, s80
	v_fmaak_f32 v21, v91, v9, 0x4b400000
	v_fmaak_f32 v22, v89, v9, 0x4b400000
	v_perm_b32 v21, v21, v22, s81
	v_or_b32_e32 v22, v21, v4
	v_fmaak_f32 v4, v90, v9, 0x4b400000
	v_fmaak_f32 v21, v87, v9, 0x4b400000
	v_perm_b32 v4, v4, v21, s80
	v_fmaak_f32 v21, v88, v9, 0x4b400000
	v_fmaak_f32 v23, v86, v9, 0x4b400000
	v_perm_b32 v21, v21, v23, s81
	v_or_b32_e32 v23, v21, v4
	v_fmaak_f32 v4, v100, v9, 0x4b400000
	v_fmaak_f32 v21, v85, v9, 0x4b400000
	v_perm_b32 v4, v4, v21, s80
	v_fmaak_f32 v21, v99, v9, 0x4b400000
	v_fmaak_f32 v24, v97, v9, 0x4b400000
	v_perm_b32 v21, v21, v24, s81
	v_or_b32_e32 v24, v21, v4
	v_fmaak_f32 v4, v98, v9, 0x4b400000
	v_fmaak_f32 v21, v95, v9, 0x4b400000
	v_perm_b32 v4, v4, v21, s80
	v_fmaak_f32 v21, v96, v9, 0x4b400000
	v_fmaak_f32 v25, v94, v9, 0x4b400000
	v_perm_b32 v21, v21, v25, s81
	v_or_b32_e32 v25, v21, v4
	v_fmaak_f32 v4, v108, v9, 0x4b400000
	v_fmaak_f32 v21, v93, v9, 0x4b400000
	global_store_dwordx4 v[152:153], v[22:25], off offset:1024
	v_perm_b32 v4, v4, v21, s80
	v_fmaak_f32 v21, v107, v9, 0x4b400000
	v_fmaak_f32 v22, v105, v9, 0x4b400000
	v_perm_b32 v21, v21, v22, s81
	v_or_b32_e32 v22, v21, v4
	v_fmaak_f32 v4, v106, v9, 0x4b400000
	v_fmaak_f32 v21, v103, v9, 0x4b400000
	v_perm_b32 v4, v4, v21, s80
	v_fmaak_f32 v21, v104, v9, 0x4b400000
	v_fmaak_f32 v23, v102, v9, 0x4b400000
	v_perm_b32 v21, v21, v23, s81
	v_or_b32_e32 v23, v21, v4
	v_fmaak_f32 v4, v116, v9, 0x4b400000
	v_fmaak_f32 v21, v101, v9, 0x4b400000
	v_perm_b32 v4, v4, v21, s80
	v_fmaak_f32 v21, v115, v9, 0x4b400000
	v_fmaak_f32 v24, v113, v9, 0x4b400000
	v_perm_b32 v21, v21, v24, s81
	v_or_b32_e32 v24, v21, v4
	v_fmaak_f32 v4, v114, v9, 0x4b400000
	v_fmaak_f32 v21, v111, v9, 0x4b400000
	v_perm_b32 v4, v4, v21, s80
	v_fmaak_f32 v21, v112, v9, 0x4b400000
	v_fmaak_f32 v25, v110, v9, 0x4b400000
	v_perm_b32 v21, v21, v25, s81
	v_or_b32_e32 v25, v21, v4
	v_or_b32_e32 v4, v149, v14
	v_lshl_add_u64 v[30:31], v[150:151], 0, v[4:5]
	v_fmaak_f32 v4, v124, v9, 0x4b400000
	v_fmaak_f32 v21, v109, v9, 0x4b400000
	global_store_dwordx4 v[30:31], v[22:25], off offset:1024
	v_perm_b32 v4, v4, v21, s80
	v_fmaak_f32 v21, v123, v9, 0x4b400000
	v_fmaak_f32 v22, v121, v9, 0x4b400000
	v_perm_b32 v21, v21, v22, s81
	v_or_b32_e32 v22, v21, v4
	v_fmaak_f32 v4, v122, v9, 0x4b400000
	v_fmaak_f32 v21, v119, v9, 0x4b400000
	v_perm_b32 v4, v4, v21, s80
	v_fmaak_f32 v21, v120, v9, 0x4b400000
	v_fmaak_f32 v23, v118, v9, 0x4b400000
	v_perm_b32 v21, v21, v23, s81
	v_or_b32_e32 v23, v21, v4
	v_fmaak_f32 v4, v132, v9, 0x4b400000
	v_fmaak_f32 v21, v117, v9, 0x4b400000
	v_perm_b32 v4, v4, v21, s80
	v_fmaak_f32 v21, v131, v9, 0x4b400000
	v_fmaak_f32 v24, v129, v9, 0x4b400000
	v_perm_b32 v21, v21, v24, s81
	v_or_b32_e32 v24, v21, v4
	v_fmaak_f32 v4, v130, v9, 0x4b400000
	v_fmaak_f32 v21, v127, v9, 0x4b400000
	v_perm_b32 v4, v4, v21, s80
	v_fmaak_f32 v21, v128, v9, 0x4b400000
	v_fmaak_f32 v25, v126, v9, 0x4b400000
	v_perm_b32 v21, v21, v25, s81
	v_or_b32_e32 v25, v21, v4
	v_fmaak_f32 v4, v140, v9, 0x4b400000
	v_fmaak_f32 v21, v125, v9, 0x4b400000
	global_store_dwordx4 v[26:27], v[22:25], off offset:1024
	v_perm_b32 v4, v4, v21, s80
	v_fmaak_f32 v21, v139, v9, 0x4b400000
	v_fmaak_f32 v22, v137, v9, 0x4b400000
	v_perm_b32 v21, v21, v22, s81
	v_or_b32_e32 v22, v21, v4
	v_fmaak_f32 v4, v138, v9, 0x4b400000
	v_fmaak_f32 v21, v135, v9, 0x4b400000
	v_perm_b32 v4, v4, v21, s80
	v_fmaak_f32 v21, v136, v9, 0x4b400000
	v_fmaak_f32 v23, v134, v9, 0x4b400000
	v_perm_b32 v21, v21, v23, s81
	v_or_b32_e32 v23, v21, v4
	v_fmaak_f32 v4, v147, v9, 0x4b400000
	v_fmaak_f32 v21, v133, v9, 0x4b400000
	v_perm_b32 v4, v4, v21, s80
	v_fmaak_f32 v21, v145, v9, 0x4b400000
	v_fmaak_f32 v24, v143, v9, 0x4b400000
	v_perm_b32 v21, v21, v24, s81
	v_or_b32_e32 v24, v21, v4
	v_fmaak_f32 v4, v144, v9, 0x4b400000
	v_fmaak_f32 v21, v142, v9, 0x4b400000
	v_fmaak_f32 v8, v8, v9, 0x4b400000
	v_fmaak_f32 v9, v141, v9, 0x4b400000
	v_perm_b32 v4, v4, v21, s80
	v_perm_b32 v8, v8, v9, s81
	v_or_b32_e32 v25, v8, v4
	global_store_dwordx4 v[28:29], v[22:25], off offset:1024
	s_barrier
	s_cbranch_scc0 .LBB0_40

.LBB0_24:
	s_or_b64 exec, exec, s[0:1]
	s_mul_i32 s0, s82, 0x2b00
	s_ashr_i32 s1, s0, 31
	s_lshl_b64 s[0:1], s[0:1], 2
	s_add_u32 s25, s10, s0
	s_addc_u32 s85, s11, s1
	s_waitcnt lgkmcnt(0)
	s_barrier
	s_and_saveexec_b64 s[0:1], s[6:7]
	s_cbranch_execz .LBB0_26
	ds_read2_b32 v[150:151], v11 offset1:32
	ds_read2_b32 v[152:153], v11 offset0:64 offset1:96
	ds_read2_b32 v[154:155], v11 offset0:128 offset1:160
	ds_read2_b32 v[156:157], v11 offset0:192 offset1:224
	s_add_u32 s34, s25, s30
	s_waitcnt lgkmcnt(3)
	v_max_f32_e32 v4, v151, v151
	v_max_f32_e32 v9, v150, v150
	v_max_f32_e32 v4, v9, v4
	s_waitcnt lgkmcnt(2)
	v_max3_f32 v4, v4, v152, v153
	s_waitcnt lgkmcnt(1)
	v_max3_f32 v4, v4, v154, v155
	s_addc_u32 s35, s85, s31
	s_waitcnt lgkmcnt(0)
	v_max3_f32 v4, v4, v156, v157
	v_lshl_add_u64 v[150:151], v[2:3], 2, s[34:35]
	global_atomic_umax v[150:151], v4, off
	s_and_b32 s21, s20, 0x80
	s_lshl_b32 s21, s21, 2
	s_and_b32 s36, s20, 0x7f
	s_lshl_b32 s36, s36, 10
	s_add_i32 s21, s21, s36
	s_add_i32 s21, s21, 0x55000
	s_add_u32 s36, s14, s21
	s_addc_u32 s37, s15, 0
	s_and_b32 s38, s2, 1
	s_lshl_b32 s38, s38, 8
	v_lshl_add_u32 v154, v11, 1, s38
	v_xor_b32_e32 v156, 0x100, v154
	v_mov_b32_e32 v155, 0
	v_mov_b32_e32 v157, 0
	v_lshl_add_u64 v[154:155], s[36:37], 0, v[154:155]
	v_lshl_add_u64 v[156:157], s[36:37], 0, v[156:157]
	s_add_i32 s38, s20, 0x1
	v_mov_b32_e32 v152, v4
	v_mov_b32_e32 v153, s38
	global_atomic_swap_x2 v[154:155], v[152:153], off
	s_mov_b32 s39, 0x80000
.Lmb_poll_0:
	global_load_dwordx2 v[150:151], v[156:157], off sc1
	s_waitcnt vmcnt(0)
	v_cmp_ne_u32_e32 vcc, s38, v151
	s_cbranch_vccz .Lmb_got_0
	s_sleep 1
	s_add_i32 s39, s39, -1
	s_cmp_lg_u32 s39, 0
	s_cbranch_scc1 .Lmb_poll_0
.Lmb_got_0:
	v_max_f32_e32 v4, v4, v150
	ds_write_b32 v11, v4 offset:1024
	s_waitcnt lgkmcnt(0)
.LBB0_26:
	s_or_b64 exec, exec, s[0:1]
	s_barrier
	s_mov_b64 s[0:1], exec
	s_branch .LBB0_9

.LBB0_42:
	s_or_b64 exec, exec, s[0:1]
	v_lshl_add_u64 v[12:13], s[24:25], 2, v[8:9]
	s_barrier
	ds_read_b32 v152, v14 offset:1024
	s_and_b64 s[0:1], s[20:21], exec
	s_cselect_b32 s0, s80, 0x15300000
	s_add_u32 s19, s14, s0
	s_addc_u32 s24, s15, 0
	s_add_i32 s25, s84, 0xffffdc00
	s_and_b64 s[0:1], s[20:21], exec
	s_cselect_b32 s20, s84, s25
	s_ashr_i32 s0, s20, 7
	v_or_b32_e32 v4, s85, v1
	s_ashr_i32 s1, s0, 31
	v_ashrrev_i32_e32 v12, 7, v4
	s_lshl_b64 s[0:1], s[0:1], 19
	v_ashrrev_i32_e32 v13, 31, v12
	s_add_u32 s0, s19, s0
	v_lshlrev_b64 v[12:13], 14, v[12:13]
	s_addc_u32 s1, s24, s1
	v_lshl_add_u64 v[12:13], s[0:1], 0, v[12:13]
	s_and_b32 s19, s20, 0x60
	v_or_b32_e32 v4, s19, v3
	v_lshlrev_b32_e32 v154, 7, v4
	v_or_b32_e32 v4, v154, v16
	s_add_i32 s18, s18, s3
	s_cmpk_lt_i32 s18, 0x220
	s_waitcnt vmcnt(0) lgkmcnt(0)
	v_max_f32_e32 v152, v152, v152
	v_max_f32_e32 v155, 0xda24260, v152
	v_div_scale_f32 v156, s[0:1], v155, v155, s81
	v_rcp_f32_e32 v157, v156
	v_lshl_add_u64 v[152:153], v[12:13], 0, v[4:5]
	v_div_scale_f32 v4, vcc, s81, v155, s81
	v_fma_f32 v158, -v156, v157, 1.0
	v_fmac_f32_e32 v157, v158, v157
	v_mul_f32_e32 v158, v4, v157
	v_fma_f32 v159, -v156, v158, v4
	v_fmac_f32_e32 v158, v159, v157
	v_fma_f32 v4, -v156, v158, v4
	v_div_fmas_f32 v4, v4, v157, v158
	v_div_fixup_f32 v155, v4, v155, s81
	v_fmaak_f32 v4, v27, v155, 0x4b400000
	v_fmaak_f32 v27, v150, v155, 0x4b400000
	v_fmaak_f32 v28, v28, v155, 0x4b400000
	v_fmaak_f32 v23, v23, v155, 0x4b400000
	v_fmaak_f32 v29, v29, v155, 0x4b400000
	v_fmaak_f32 v24, v24, v155, 0x4b400000
	v_fmaak_f32 v30, v30, v155, 0x4b400000
	v_fmaak_f32 v25, v25, v155, 0x4b400000
	v_fmaak_f32 v35, v35, v155, 0x4b400000
	v_fmaak_f32 v26, v26, v155, 0x4b400000
	v_fmaak_f32 v36, v36, v155, 0x4b400000
	v_fmaak_f32 v32, v32, v155, 0x4b400000
	v_fmaak_f32 v37, v37, v155, 0x4b400000
	v_fmaak_f32 v33, v33, v155, 0x4b400000
	v_fmaak_f32 v38, v38, v155, 0x4b400000
	v_fmaak_f32 v34, v34, v155, 0x4b400000
	v_fmaak_f32 v46, v46, v155, 0x4b400000
	v_fmaak_f32 v31, v31, v155, 0x4b400000
	v_fmaak_f32 v45, v45, v155, 0x4b400000
	v_fmaak_f32 v43, v43, v155, 0x4b400000
	v_fmaak_f32 v44, v44, v155, 0x4b400000
	v_fmaak_f32 v41, v41, v155, 0x4b400000
	v_fmaak_f32 v42, v42, v155, 0x4b400000
	v_fmaak_f32 v40, v40, v155, 0x4b400000
	v_perm_b32 v4, v4, v27, s82
	v_perm_b32 v23, v28, v23, s83
	v_perm_b32 v27, v29, v24, s82
	v_perm_b32 v25, v30, v25, s83
	v_perm_b32 v26, v35, v26, s82
	v_perm_b32 v28, v36, v32, s83
	v_perm_b32 v29, v37, v33, s82
	v_perm_b32 v30, v38, v34, s83
	v_perm_b32 v31, v46, v31, s82
	v_perm_b32 v32, v45, v43, s83
	v_perm_b32 v33, v44, v41, s82
	v_perm_b32 v34, v42, v40, s83
	v_or_b32_e32 v24, v23, v4
	v_add_u32_e32 v4, v154, v16
	v_or_b32_e32 v25, v25, v27
	v_or_b32_e32 v26, v28, v26
	v_or_b32_e32 v27, v30, v29
	v_or_b32_e32 v28, v32, v31
	v_or_b32_e32 v29, v34, v33
	v_lshl_add_u64 v[32:33], v[12:13], 0, v[4:5]
	v_fmaak_f32 v4, v62, v155, 0x4b400000
	v_fmaak_f32 v23, v47, v155, 0x4b400000
	global_store_dwordx4 v[152:153], v[24:27], off
	v_perm_b32 v4, v4, v23, s82
	v_fmaak_f32 v23, v61, v155, 0x4b400000
	v_fmaak_f32 v24, v59, v155, 0x4b400000
	v_perm_b32 v23, v23, v24, s83
	v_or_b32_e32 v24, v23, v4
	v_fmaak_f32 v4, v60, v155, 0x4b400000
	v_fmaak_f32 v23, v57, v155, 0x4b400000
	v_perm_b32 v4, v4, v23, s82
	v_fmaak_f32 v23, v58, v155, 0x4b400000
	v_fmaak_f32 v25, v56, v155, 0x4b400000
	v_perm_b32 v23, v23, v25, s83
	v_or_b32_e32 v25, v23, v4
	v_fmaak_f32 v4, v70, v155, 0x4b400000
	v_fmaak_f32 v23, v55, v155, 0x4b400000
	v_perm_b32 v4, v4, v23, s82
	v_fmaak_f32 v23, v69, v155, 0x4b400000
	v_fmaak_f32 v26, v67, v155, 0x4b400000
	v_perm_b32 v23, v23, v26, s83
	v_or_b32_e32 v26, v23, v4
	v_fmaak_f32 v4, v68, v155, 0x4b400000
	v_fmaak_f32 v23, v65, v155, 0x4b400000
	v_fmaak_f32 v54, v54, v155, 0x4b400000
	v_fmaak_f32 v39, v39, v155, 0x4b400000
	v_fmaak_f32 v53, v53, v155, 0x4b400000
	v_fmaak_f32 v51, v51, v155, 0x4b400000
	v_fmaak_f32 v52, v52, v155, 0x4b400000
	v_fmaak_f32 v49, v49, v155, 0x4b400000
	v_fmaak_f32 v50, v50, v155, 0x4b400000
	v_fmaak_f32 v48, v48, v155, 0x4b400000
	v_perm_b32 v4, v4, v23, s82
	v_fmaak_f32 v23, v66, v155, 0x4b400000
	v_fmaak_f32 v27, v64, v155, 0x4b400000
	v_perm_b32 v35, v54, v39, s82
	v_perm_b32 v36, v53, v51, s83
	v_perm_b32 v37, v52, v49, s82
	v_perm_b32 v38, v50, v48, s83
	v_perm_b32 v23, v23, v27, s83
	v_or_b32_e32 v30, v36, v35
	v_or_b32_e32 v31, v38, v37
	v_or_b32_e32 v27, v23, v4
	v_or_b32_e32 v4, v154, v18
	global_store_dwordx4 v[32:33], v[28:31], off offset:16
	v_fmaak_f32 v23, v63, v155, 0x4b400000
	s_nop 0
	v_lshl_add_u64 v[28:29], v[12:13], 0, v[4:5]
	v_fmaak_f32 v4, v78, v155, 0x4b400000
	global_store_dwordx4 v[28:29], v[24:27], off
	v_perm_b32 v4, v4, v23, s82
	v_fmaak_f32 v23, v77, v155, 0x4b400000
	v_fmaak_f32 v24, v75, v155, 0x4b400000
	v_perm_b32 v23, v23, v24, s83
	v_or_b32_e32 v24, v23, v4
	v_fmaak_f32 v4, v76, v155, 0x4b400000
	v_fmaak_f32 v23, v73, v155, 0x4b400000
	v_perm_b32 v4, v4, v23, s82
	v_fmaak_f32 v23, v74, v155, 0x4b400000
	v_fmaak_f32 v25, v72, v155, 0x4b400000
	v_perm_b32 v23, v23, v25, s83
	v_or_b32_e32 v25, v23, v4
	v_fmaak_f32 v4, v86, v155, 0x4b400000
	v_fmaak_f32 v23, v71, v155, 0x4b400000
	v_perm_b32 v4, v4, v23, s82
	v_fmaak_f32 v23, v85, v155, 0x4b400000
	v_fmaak_f32 v26, v83, v155, 0x4b400000
	v_perm_b32 v23, v23, v26, s83
	v_or_b32_e32 v26, v23, v4
	v_fmaak_f32 v4, v84, v155, 0x4b400000
	v_fmaak_f32 v23, v81, v155, 0x4b400000
	v_perm_b32 v4, v4, v23, s82
	v_fmaak_f32 v23, v82, v155, 0x4b400000
	v_fmaak_f32 v27, v80, v155, 0x4b400000
	v_perm_b32 v23, v23, v27, s83
	v_or_b32_e32 v27, v23, v4
	v_or_b32_e32 v4, v154, v19
	v_lshl_add_u64 v[28:29], v[12:13], 0, v[4:5]
	v_fmaak_f32 v4, v94, v155, 0x4b400000
	v_fmaak_f32 v23, v79, v155, 0x4b400000
	global_store_dwordx4 v[28:29], v[24:27], off
	v_perm_b32 v4, v4, v23, s82
	v_fmaak_f32 v23, v93, v155, 0x4b400000
	v_fmaak_f32 v24, v91, v155, 0x4b400000
	v_perm_b32 v23, v23, v24, s83
	v_or_b32_e32 v24, v23, v4
	v_fmaak_f32 v4, v92, v155, 0x4b400000
	v_fmaak_f32 v23, v89, v155, 0x4b400000
	v_perm_b32 v4, v4, v23, s82
	v_fmaak_f32 v23, v90, v155, 0x4b400000
	v_fmaak_f32 v25, v88, v155, 0x4b400000
	v_perm_b32 v23, v23, v25, s83
	v_or_b32_e32 v25, v23, v4
	v_fmaak_f32 v4, v102, v155, 0x4b400000
	v_fmaak_f32 v23, v87, v155, 0x4b400000
	v_perm_b32 v4, v4, v23, s82
	v_fmaak_f32 v23, v101, v155, 0x4b400000
	v_fmaak_f32 v26, v99, v155, 0x4b400000
	v_perm_b32 v23, v23, v26, s83
	v_or_b32_e32 v26, v23, v4
	v_fmaak_f32 v4, v100, v155, 0x4b400000
	v_fmaak_f32 v23, v97, v155, 0x4b400000
	v_perm_b32 v4, v4, v23, s82
	v_fmaak_f32 v23, v98, v155, 0x4b400000
	v_fmaak_f32 v27, v96, v155, 0x4b400000
	v_perm_b32 v23, v23, v27, s83
	v_or_b32_e32 v27, v23, v4
	v_fmaak_f32 v4, v110, v155, 0x4b400000
	v_fmaak_f32 v23, v95, v155, 0x4b400000
	global_store_dwordx4 v[32:33], v[24:27], off offset:1024
	v_perm_b32 v4, v4, v23, s82
	v_fmaak_f32 v23, v109, v155, 0x4b400000
	v_fmaak_f32 v24, v107, v155, 0x4b400000
	v_perm_b32 v23, v23, v24, s83
	v_or_b32_e32 v24, v23, v4
	v_fmaak_f32 v4, v108, v155, 0x4b400000
	v_fmaak_f32 v23, v105, v155, 0x4b400000
	v_perm_b32 v4, v4, v23, s82
	v_fmaak_f32 v23, v106, v155, 0x4b400000
	v_fmaak_f32 v25, v104, v155, 0x4b400000
	v_perm_b32 v23, v23, v25, s83
	v_or_b32_e32 v25, v23, v4
	v_fmaak_f32 v4, v118, v155, 0x4b400000
	v_fmaak_f32 v23, v103, v155, 0x4b400000
	v_perm_b32 v4, v4, v23, s82
	v_fmaak_f32 v23, v117, v155, 0x4b400000
	v_fmaak_f32 v26, v115, v155, 0x4b400000
	v_perm_b32 v23, v23, v26, s83
	v_or_b32_e32 v26, v23, v4
	v_fmaak_f32 v4, v116, v155, 0x4b400000
	v_fmaak_f32 v23, v113, v155, 0x4b400000
	v_perm_b32 v4, v4, v23, s82
	v_fmaak_f32 v23, v114, v155, 0x4b400000
	v_fmaak_f32 v27, v112, v155, 0x4b400000
	v_perm_b32 v23, v23, v27, s83
	v_or_b32_e32 v27, v23, v4
	v_add_u32_e32 v4, v154, v17
	v_lshl_add_u64 v[28:29], v[12:13], 0, v[4:5]
	v_fmaak_f32 v4, v126, v155, 0x4b400000
	v_fmaak_f32 v23, v111, v155, 0x4b400000
	global_store_dwordx4 v[28:29], v[24:27], off offset:1024
	v_perm_b32 v4, v4, v23, s82
	v_fmaak_f32 v23, v125, v155, 0x4b400000
	v_fmaak_f32 v24, v123, v155, 0x4b400000
	v_perm_b32 v23, v23, v24, s83
	v_or_b32_e32 v24, v23, v4
	v_fmaak_f32 v4, v124, v155, 0x4b400000
	v_fmaak_f32 v23, v121, v155, 0x4b400000
	v_perm_b32 v4, v4, v23, s82
	v_fmaak_f32 v23, v122, v155, 0x4b400000
	v_fmaak_f32 v25, v120, v155, 0x4b400000
	v_perm_b32 v23, v23, v25, s83
	v_or_b32_e32 v25, v23, v4
	v_fmaak_f32 v4, v134, v155, 0x4b400000
	v_fmaak_f32 v23, v119, v155, 0x4b400000
	v_perm_b32 v4, v4, v23, s82
	v_fmaak_f32 v23, v133, v155, 0x4b400000
	v_fmaak_f32 v26, v131, v155, 0x4b400000
	v_perm_b32 v23, v23, v26, s83
	v_or_b32_e32 v26, v23, v4
	v_fmaak_f32 v4, v132, v155, 0x4b400000
	v_fmaak_f32 v23, v129, v155, 0x4b400000
	v_perm_b32 v4, v4, v23, s82
	v_fmaak_f32 v23, v130, v155, 0x4b400000
	v_fmaak_f32 v27, v128, v155, 0x4b400000
	v_perm_b32 v23, v23, v27, s83
	v_or_b32_e32 v27, v23, v4
	v_add_u32_e32 v4, v154, v18
	v_lshl_add_u64 v[28:29], v[12:13], 0, v[4:5]
	v_fmaak_f32 v4, v142, v155, 0x4b400000
	v_fmaak_f32 v23, v127, v155, 0x4b400000
	global_store_dwordx4 v[28:29], v[24:27], off offset:1024
	v_perm_b32 v4, v4, v23, s82
	v_fmaak_f32 v23, v141, v155, 0x4b400000
	v_fmaak_f32 v24, v139, v155, 0x4b400000
	v_perm_b32 v23, v23, v24, s83
	v_or_b32_e32 v24, v23, v4
	v_fmaak_f32 v4, v140, v155, 0x4b400000
	v_fmaak_f32 v23, v137, v155, 0x4b400000
	v_perm_b32 v4, v4, v23, s82
	v_fmaak_f32 v23, v138, v155, 0x4b400000
	v_fmaak_f32 v25, v136, v155, 0x4b400000
	v_perm_b32 v23, v23, v25, s83
	v_or_b32_e32 v25, v23, v4
	v_fmaak_f32 v4, v149, v155, 0x4b400000
	v_fmaak_f32 v23, v135, v155, 0x4b400000
	v_perm_b32 v4, v4, v23, s82
	v_fmaak_f32 v23, v148, v155, 0x4b400000
	v_fmaak_f32 v26, v145, v155, 0x4b400000
	v_perm_b32 v23, v23, v26, s83
	v_or_b32_e32 v26, v23, v4
	v_fmaak_f32 v4, v147, v155, 0x4b400000
	v_fmaak_f32 v23, v144, v155, 0x4b400000
	v_perm_b32 v4, v4, v23, s82
	v_fmaak_f32 v23, v151, v155, 0x4b400000
	v_fmaak_f32 v27, v143, v155, 0x4b400000
	v_perm_b32 v23, v23, v27, s83
	v_or_b32_e32 v27, v23, v4
	v_add_u32_e32 v4, v154, v19
	v_lshl_add_u64 v[12:13], v[12:13], 0, v[4:5]
	global_store_dwordx4 v[12:13], v[24:27], off offset:1024
	s_barrier
	s_cbranch_scc0 .LBB0_61

.LBB0_45:
	s_or_b64 exec, exec, s[0:1]
	s_waitcnt lgkmcnt(0)
	s_barrier
	s_and_saveexec_b64 s[0:1], s[6:7]
	s_cbranch_execz .LBB0_47
	ds_read2_b32 v[12:13], v15 offset1:32
	ds_read2_b32 v[152:153], v15 offset0:64 offset1:96
	ds_read2_b32 v[154:155], v15 offset0:128 offset1:160
	ds_read2_b32 v[156:157], v15 offset0:192 offset1:224
	s_waitcnt lgkmcnt(3)
	v_max_f32_e32 v4, v13, v13
	v_max_f32_e32 v12, v12, v12
	v_max_f32_e32 v4, v12, v4
	s_waitcnt lgkmcnt(2)
	v_max3_f32 v4, v4, v152, v153
	s_waitcnt lgkmcnt(1)
	v_max3_f32 v4, v4, v154, v155
	s_waitcnt lgkmcnt(0)
	v_max3_f32 v4, v4, v156, v157
	v_lshl_add_u64 v[12:13], s[24:25], 2, v[6:7]
	global_atomic_umax v[12:13], v4, off
	s_and_b32 s19, s18, 0x80
	s_lshl_b32 s19, s19, 2
	s_and_b32 s34, s18, 0x7f
	s_lshl_b32 s34, s34, 10
	s_add_i32 s19, s19, s34
	s_add_i32 s19, s19, 0xc1000
	s_add_u32 s34, s14, s19
	s_addc_u32 s35, s15, 0
	s_and_b32 s30, s2, 1
	s_lshl_b32 s30, s30, 8
	v_lshl_add_u32 v154, v15, 1, s30
	v_xor_b32_e32 v156, 0x100, v154
	v_mov_b32_e32 v155, 0
	v_mov_b32_e32 v157, 0
	v_lshl_add_u64 v[154:155], s[34:35], 0, v[154:155]
	v_lshl_add_u64 v[156:157], s[34:35], 0, v[156:157]
	s_add_i32 s30, s18, 0x1
	v_mov_b32_e32 v152, v4
	v_mov_b32_e32 v153, s30
	global_atomic_swap_x2 v[154:155], v[152:153], off
	s_mov_b32 s31, 0x80000
.Lmb_poll_1:
	global_load_dwordx2 v[12:13], v[156:157], off sc1
	s_waitcnt vmcnt(0)
	v_cmp_ne_u32_e32 vcc, s30, v13
	s_cbranch_vccz .Lmb_got_1
	s_sleep 1
	s_add_i32 s31, s31, -1
	s_cmp_lg_u32 s31, 0
	s_cbranch_scc1 .Lmb_poll_1
.Lmb_got_1:
	v_max_f32_e32 v4, v4, v12
	ds_write_b32 v15, v4 offset:1024
	s_waitcnt lgkmcnt(0)
